# plus: GEMM prologues issue the K-tile-1 staging loads before the first wait so both batches overlap
# speedup vs baseline: 1.0070x; 1.0070x over previous
; #define PG8_STAGE(bufoff, gbase, voff) do { _Pragma("unroll") for (int _i = 0; _i < 2; ++_i) \
;         __builtin_amdgcn_global_load_lds((const unsigned*)((const char*)(gbase) + (voff)[_i]), (PG8_LAS unsigned*)(lds + (bufoff) + ldsw + _i * 8192), 16, 0, 0); } while (0)
; #define PG8_WAIT_V(n) asm volatile("s_waitcnt vmcnt(" #n ")" ::: "memory")
; #define PG8_BAR __builtin_amdgcn_s_barrier()
; template <class Epi, class Sched, bool ALIGN_EPI = false, bool SP2 = false>
; __device__ __forceinline__ void gemm_phase(PG8_LAS unsigned char* lds, const Gemm g, const Sched& S, const Epi& E) {
;     ...
;     for (int i = 0; i < 2; ++i) { int R, C; stage_rc(tid * 16 + i * 8192, R, C); const int Rb = Epi::PERM ? ((R & ~31) + perm32(R & 31)) : R;
;         voffA[i] = (unsigned)(R * K + C) * 2u; voffB[i] = (unsigned)(Rb * K + C) * 2u; }
;     const size_t kstep = (size_t)(BK * 2);
;     const size_t hstep = (size_t)HALF * K * 2;
;     const size_t tstep = 2 * hstep;
;     const unsigned ldsw = (unsigned)wid * 1024u;
;     const int aoff = lds_byte(wr * 64 + fr, fq * 8), boff = lds_byte(wc * 32 + fr, fq * 8);
;     ...
;         PG8_STAGE(PG8_SB(0, 0), cB, voffB); PG8_STAGE(PG8_SB(0, 1), cB + hstep, voffB); PG8_STAGE(PG8_SA(0, 0), cA, voffA); PG8_STAGE(PG8_SA(0, 1), cA + hstep, voffA);
;         if (wr == 1) PG8_BAR;
;         PG8_WAIT_V(2); PG8_BAR;
;         PG8_STAGE(PG8_SB(1, 0), cB + kstep, voffB); PG8_STAGE(PG8_SA(1, 0), cA + kstep, voffA); PG8_STAGE(PG8_SB(1, 1), cB + hstep + kstep, voffB);
;         PG8_WAIT_V(6); PG8_BAR;
.LBB0_207:
	v_readlane_b32 s14, v253, 34
	v_readlane_b32 s15, v253, 35
	v_readlane_b32 s16, v253, 46
	s_lshl_b64 s[8:9], s[14:15], 2
	v_readlane_b32 s17, v253, 47
	v_readlane_b32 s18, v253, 48
	v_readlane_b32 s19, v253, 49
	s_add_u32 s8, s18, s8
	v_readlane_b32 s16, v253, 63
	s_addc_u32 s9, s19, s9
	v_readlane_b32 s17, v254, 0
	s_lshl_b32 s14, s16, 6
	s_lshl_b64 s[14:15], s[14:15], 2
	v_readlane_b32 s16, v253, 44
	v_bfe_u32 v16, v0, 4, 2
	v_readlane_b32 s17, v253, 45
	s_add_u32 s14, s16, s14
	v_and_b32_e32 v147, 15, v0
	v_lshlrev_b32_e32 v18, 4, v16
	v_lshlrev_b32_e32 v0, 2, v0
	s_addc_u32 s15, s17, s15
	s_and_b32 s65, s5, 3
	s_lshl_b32 s66, s4, 6
	v_lshl_or_b32 v18, v147, 6, v18
	s_lshl_b32 s4, s4, 13
	v_and_b32_e32 v0, 32, v0
	v_bitop3_b32 v19, v18, s4, v0 bitop3:0xde
	s_lshl_b32 s4, s65, 12
	v_bitop3_b32 v196, v18, s4, v0 bitop3:0xde
	s_add_u32 s4, s2, 0x35420000
	s_addc_u32 s5, s3, 0
	s_add_u32 s18, s2, 0x19c00000
	s_addc_u32 s19, s3, 0
	s_add_u32 s20, s2, 0x35400000
	s_addc_u32 s21, s3, 0
	s_add_u32 s22, s2, 0x35500000
	s_addc_u32 s23, s3, 0
	s_add_u32 s67, s2, 0x35b00000
	s_mov_b64 s[16:17], 0x80
	s_addc_u32 s68, s3, 0
	s_add_i32 m0, s61, 0x18000
	v_lshl_add_u64 v[8:9], v[8:9], 0, s[16:17]
	global_load_lds_dwordx4 v[8:9], off
	v_lshl_add_u64 v[6:7], v[6:7], 0, s[16:17]
	s_add_i32 m0, s61, 0x1a000
	s_add_i32 s69, s61, 0x8000
	global_load_lds_dwordx4 v[6:7], off
	v_lshl_add_u64 v[2:3], v[2:3], 0, s[16:17]
	s_mov_b32 m0, s69
	s_add_i32 s70, s61, 0xa000
	global_load_lds_dwordx4 v[2:3], off
	v_lshl_add_u64 v[2:3], v[4:5], 0, s[16:17]
	s_add_u32 s16, s10, 0x80080
	s_mov_b32 m0, s70
	s_addc_u32 s17, s11, 0
	global_load_lds_dwordx4 v[2:3], off
	s_add_i32 m0, s61, 0x1c000
	v_lshl_add_u64 v[2:3], s[16:17], 0, v[142:143]
	global_load_lds_dwordx4 v[2:3], off
	v_lshl_add_u64 v[2:3], s[16:17], 0, v[138:139]
	s_add_i32 m0, s61, 0x1e000
	v_lshlrev_b32_e32 v17, 3, v16
	global_load_lds_dwordx4 v[2:3], off
	s_waitcnt vmcnt(8)
	s_barrier
	v_lshl_or_b32 v146, s65, 5, v17
	v_lshlrev_b32_e32 v0, 1, v146
	v_lshl_add_u64 v[2:3], s[2:3], 0, v[0:1]
	s_mov_b64 s[16:17], 0x35900000
	v_lshlrev_b32_e32 v0, 2, v146
	v_lshl_add_u64 v[148:149], v[2:3], 0, s[16:17]
	v_lshl_add_u64 v[2:3], s[2:3], 0, v[0:1]
	v_lshl_add_u64 v[152:153], s[14:15], 0, v[0:1]
	v_lshl_add_u64 v[154:155], s[8:9], 0, v[0:1]
	v_lshlrev_b32_e32 v0, 15, v10
	s_mov_b64 s[16:17], 0x100000
	v_and_b32_e32 v0, 0xffff0000, v0
	v_lshl_add_u64 v[150:151], v[2:3], 0, s[16:17]
	v_lshl_add_u32 v0, v11, 12, v0
	v_and_b32_e32 v2, 1, v10
	v_lshl_or_b32 v0, v2, 6, v0
	v_lshl_add_u32 v156, v12, 1, v0
	v_lshlrev_b32_e32 v0, 15, v14
	v_and_b32_e32 v0, 0xffff0000, v0
	s_waitcnt vmcnt(6)
	s_cmpk_lt_u32 s6, 0x100
	v_lshl_add_u32 v0, v13, 12, v0
	v_and_b32_e32 v2, 1, v14
	s_cselect_b64 s[24:25], -1, 0
	s_cmp_lt_u32 s65, 2
	v_lshl_or_b32 v0, v2, 6, v0
	v_readlane_b32 s8, v253, 36
	s_cselect_b64 s[26:27], -1, 0
	s_mov_b32 s71, 0
	v_cmp_eq_u32_e64 s[6:7], 0, v16
	v_mov_b32_e32 v157, v1
	v_lshl_add_u32 v158, v15, 1, v0
	v_mov_b32_e32 v159, v1
	v_add_u32_e32 v197, 0, v19
	v_readlane_b32 s52, v253, 22
	s_mov_b32 s42, s8
	s_barrier
	v_readlane_b32 s9, v253, 37
	s_branch .LBB0_210

; #define PG8_STAGE(bufoff, gbase, voff) do { _Pragma("unroll") for (int _i = 0; _i < 2; ++_i) \
;         __builtin_amdgcn_global_load_lds((const unsigned*)((const char*)(gbase) + (voff)[_i]), (PG8_LAS unsigned*)(lds + (bufoff) + ldsw + _i * 8192), 16, 0, 0); } while (0)
; #define PG8_WAIT_V(n) asm volatile("s_waitcnt vmcnt(" #n ")" ::: "memory")
; #define PG8_BAR __builtin_amdgcn_s_barrier()
; template <class Epi, class Sched, bool ALIGN_EPI = false, bool SP2 = false>
; __device__ __forceinline__ void gemm_phase(PG8_LAS unsigned char* lds, const Gemm g, const Sched& S, const Epi& E) {
;     ...
;         PG8_STAGE(PG8_SB(0, 0), cB, voffB); PG8_STAGE(PG8_SB(0, 1), cB + hstep, voffB); PG8_STAGE(PG8_SA(0, 0), cA, voffA); PG8_STAGE(PG8_SA(0, 1), cA + hstep, voffA);
;         if (wr == 1) PG8_BAR;
;         PG8_WAIT_V(2); PG8_BAR;
;         PG8_STAGE(PG8_SB(1, 0), cB + kstep, voffB); PG8_STAGE(PG8_SA(1, 0), cA + kstep, voffA); PG8_STAGE(PG8_SB(1, 1), cB + hstep + kstep, voffB);
;         PG8_WAIT_V(6); PG8_BAR;
;     __device__ __forceinline__ void operator()(const pg8::f32x4 (&acc)[2][2][4][2], const pg8::Unit& u, int wr, int wc, int fr, int fq) const {
;     ...
;         const int src4 = (16 * (fr & 3) + 4 * fq + (fr >> 2)) * 4;
;         const int row0 = (u.pm & 31) * 256 + wr * 64 + 4 * fq + (fr >> 2), col0 = (u.pn & 7) * 256 + wc * 32 + 8 * (fr & 3);
.LBB0_1107:
	s_add_u32 s2, s8, 0x2f400000
	s_addc_u32 s3, s9, 0
	s_add_u32 s4, s8, 0x33400000
	s_addc_u32 s5, s9, 0
	s_add_u32 s14, s22, 0x80080
	s_addc_u32 s15, s23, 0
	s_add_u32 s6, s8, 0x19c06c00
	s_addc_u32 s7, s9, 0
	s_add_u32 s8, s8, 0x19c07c00
	s_mov_b64 s[16:17], 0x80
	s_addc_u32 s9, s9, 0
	s_add_i32 m0, s34, 0x18000
	v_lshl_add_u64 v[8:9], v[8:9], 0, s[16:17]
	global_load_lds_dwordx4 v[8:9], off
	v_lshl_add_u64 v[6:7], v[6:7], 0, s[16:17]
	s_add_i32 m0, s34, 0x1a000
	s_add_i32 s38, s34, 0x8000
	global_load_lds_dwordx4 v[6:7], off
	v_lshl_add_u64 v[2:3], v[2:3], 0, s[16:17]
	s_mov_b32 m0, s38
	s_add_i32 s39, s34, 0xa000
	global_load_lds_dwordx4 v[2:3], off
	v_lshl_add_u64 v[2:3], v[4:5], 0, s[16:17]
	s_mov_b32 m0, s39
	v_bfe_u32 v17, v0, 4, 2
	global_load_lds_dwordx4 v[2:3], off
	s_add_i32 m0, s34, 0x1c000
	v_lshl_add_u64 v[2:3], s[14:15], 0, v[146:147]
	global_load_lds_dwordx4 v[2:3], off
	v_lshl_add_u64 v[2:3], s[14:15], 0, v[142:143]
	s_add_i32 m0, s34, 0x1e000
	v_and_b32_e32 v16, 15, v0
	global_load_lds_dwordx4 v[2:3], off
	s_waitcnt vmcnt(8)
	s_barrier
	v_lshlrev_b32_e32 v18, 4, v17
	v_lshl_or_b32 v16, v16, 6, v18
	v_lshlrev_b32_e32 v18, 2, v0
	v_and_b32_e32 v2, 3, v0
	v_bfe_u32 v0, v0, 2, 2
	v_lshl_or_b32 v0, v17, 2, v0
	s_lshl_b32 s13, s12, 13
	v_and_b32_e32 v18, 32, v18
	s_lshl_b32 s11, s11, 5
	v_lshlrev_b32_e32 v3, 2, v0
	v_lshl_or_b32 v180, s12, 6, v0
	v_lshlrev_b32_e32 v0, 15, v10
	v_bitop3_b32 v19, v16, s13, v18 bitop3:0xde
	s_and_b32 s13, s11, 0x60
	v_and_b32_e32 v0, 0xffff0000, v0
	v_lshl_or_b32 v179, v2, 6, v3
	v_lshl_or_b32 v181, v2, 3, s13
	v_lshl_add_u32 v0, v11, 12, v0
	v_and_b32_e32 v2, 1, v10
	v_lshl_or_b32 v0, v2, 6, v0
	v_lshl_add_u32 v150, v12, 1, v0
	v_lshlrev_b32_e32 v0, 15, v14
	v_and_b32_e32 v0, 0xffff0000, v0
	s_lshl_b32 s11, s13, 7
	s_waitcnt vmcnt(6)
	v_lshl_add_u32 v0, v13, 12, v0
	v_and_b32_e32 v2, 1, v14
	s_cmpk_lt_u32 s10, 0x100
	v_lshl_or_b32 v0, v2, 6, v0
	v_readlane_b32 s12, v253, 15
	v_bitop3_b32 v178, v16, s11, v18 bitop3:0xde
	s_cselect_b64 s[10:11], -1, 0
	v_mov_b32_e32 v151, v1
	v_lshl_add_u32 v152, v15, 1, v0
	v_mov_b32_e32 v153, v1
	s_mov_b32 s40, 0
	v_add_u32_e32 v182, 0, v19
	v_readlane_b32 s41, v253, 19
	s_mov_b32 s42, s12
	s_barrier
	v_readlane_b32 s13, v253, 16
	s_branch .LBB0_1110

; #define PG8_STAGE(bufoff, gbase, voff) do { _Pragma("unroll") for (int _i = 0; _i < 2; ++_i) \
;         __builtin_amdgcn_global_load_lds((const unsigned*)((const char*)(gbase) + (voff)[_i]), (PG8_LAS unsigned*)(lds + (bufoff) + ldsw + _i * 8192), 16, 0, 0); } while (0)
; #define PG8_WAIT_V(n) asm volatile("s_waitcnt vmcnt(" #n ")" ::: "memory")
; #define PG8_BAR __builtin_amdgcn_s_barrier()
; template <class Epi, class Sched, bool ALIGN_EPI = false, bool SP2 = false>
; __device__ __forceinline__ void gemm_phase(PG8_LAS unsigned char* lds, const Gemm g, const Sched& S, const Epi& E) {
;     ...
;         PG8_STAGE(PG8_SB(0, 0), cB, voffB); PG8_STAGE(PG8_SB(0, 1), cB + hstep, voffB); PG8_STAGE(PG8_SA(0, 0), cA, voffA); PG8_STAGE(PG8_SA(0, 1), cA + hstep, voffA);
;         if (wr == 1) PG8_BAR;
;         PG8_WAIT_V(2); PG8_BAR;
;         PG8_STAGE(PG8_SB(1, 0), cB + kstep, voffB); PG8_STAGE(PG8_SA(1, 0), cA + kstep, voffA); PG8_STAGE(PG8_SB(1, 1), cB + hstep + kstep, voffB);
;         PG8_WAIT_V(6); PG8_BAR;
;     __device__ __forceinline__ void operator()(const pg8::f32x4 (&acc)[2][2][4][2], const pg8::Unit& u, int wr, int wc, int fr, int fq) const {
;         const int src4 = (16 * (fr & 3) + 4 * fq + (fr >> 2)) * 4;
;         const int row0 = u.pm * 256 + wr * 64 + 4 * fq + (fr >> 2), col0 = u.pn * 256 + wc * 32 + 8 * (fr & 3);
.LBB0_1172:
	s_add_u32 s12, s0, 0x17c00000
	v_bfe_u32 v18, v10, 4, 2
	s_addc_u32 s13, s1, 0
	v_and_b32_e32 v17, 15, v10
	v_lshlrev_b32_e32 v19, 4, v18
	s_add_u32 s14, s0, 0x3bb00000
	v_lshl_or_b32 v17, v17, 6, v19
	v_lshlrev_b32_e32 v19, 2, v10
	s_addc_u32 s15, s1, 0
	s_and_b32 s40, s16, 3
	s_lshl_b32 s0, s3, 13
	v_and_b32_e32 v19, 32, v19
	v_bitop3_b32 v20, v17, s0, v19 bitop3:0xde
	s_lshl_b32 s0, s40, 12
	v_bitop3_b32 v232, v17, s0, v19 bitop3:0xde
	s_mov_b64 s[0:1], 0x80
	s_add_i32 m0, s36, 0x18000
	v_lshl_add_u64 v[8:9], v[8:9], 0, s[0:1]
	global_load_lds_dwordx4 v[8:9], off
	v_lshl_add_u64 v[6:7], v[6:7], 0, s[0:1]
	s_add_i32 m0, s36, 0x1a000
	s_add_i32 s41, s36, 0x8000
	global_load_lds_dwordx4 v[6:7], off
	v_lshl_add_u64 v[2:3], v[2:3], 0, s[0:1]
	s_mov_b32 m0, s41
	s_add_i32 s42, s36, 0xa000
	global_load_lds_dwordx4 v[2:3], off
	v_lshl_add_u64 v[2:3], v[4:5], 0, s[0:1]
	s_add_u32 s0, s4, 0x80080
	s_mov_b32 m0, s42
	s_addc_u32 s1, s5, 0
	global_load_lds_dwordx4 v[2:3], off
	s_add_i32 m0, s36, 0x1c000
	v_lshl_add_u64 v[2:3], s[0:1], 0, v[0:1]
	global_load_lds_dwordx4 v[2:3], off
	v_lshl_add_u64 v[2:3], s[0:1], 0, v[194:195]
	s_add_i32 m0, s36, 0x1e000
	s_cmpk_lt_u32 s2, 0x100
	global_load_lds_dwordx4 v[2:3], off
	s_waitcnt vmcnt(8)
	s_barrier
	v_bfe_u32 v3, v10, 2, 2
	v_lshl_or_b32 v3, v18, 2, v3
	v_and_b32_e32 v2, 3, v10
	v_lshlrev_b32_e32 v4, 2, v3
	v_lshl_or_b32 v233, v2, 6, v4
	v_lshl_or_b32 v234, s3, 6, v3
	v_lshlrev_b32_e32 v3, 3, v2
	v_cmp_eq_u32_e64 s[0:1], 0, v2
	v_lshlrev_b32_e32 v2, 15, v11
	v_and_b32_e32 v2, 0xffff0000, v2
	v_lshl_or_b32 v235, s40, 5, v3
	v_lshl_add_u32 v2, v12, 12, v2
	v_and_b32_e32 v3, 1, v11
	v_lshl_or_b32 v2, v3, 6, v2
	v_lshl_add_u32 v200, v13, 1, v2
	v_lshlrev_b32_e32 v2, 15, v15
	v_and_b32_e32 v2, 0xffff0000, v2
	s_waitcnt vmcnt(6)
	v_lshl_add_u32 v2, v14, 12, v2
	v_and_b32_e32 v3, 1, v15
	v_lshl_or_b32 v2, v3, 6, v2
	v_readlane_b32 s2, v253, 40
	s_cselect_b64 s[16:17], -1, 0
	s_mov_b32 s43, 0
	v_mov_b32_e32 v201, v1
	v_lshl_add_u32 v202, v16, 1, v2
	v_mov_b32_e32 v203, v1
	v_add_u32_e32 v236, 0, v20
	v_readlane_b32 s44, v253, 23
	s_mov_b32 s45, s2
	s_barrier
	v_readlane_b32 s3, v253, 41
	s_branch .LBB0_1175
